# SwiGLU K-loop load segments trimmed: LDS-DMA via scalar base + 32-bit lane offset (12 fewer 64-bit VALU adds per iteration), pointer selects moved behind the LDS reads, first-iteration test removed fr
# speedup vs baseline: 1.0126x; 1.0008x over previous
; #define PG8_STAGE(bufoff, gbase, voff) do { _Pragma("unroll") for (int _i = 0; _i < 2; ++_i) \
;         __builtin_amdgcn_global_load_lds((const unsigned*)((const char*)(gbase) + (voff)[_i]), (LAS unsigned*)(lds + (bufoff) + ldsw + _i * 8192), 16, 0, 0); } while (0)
; #define PG8_LDA(dst, b, h) do { _Pragma("unroll") for (int m = 0; m < 4; ++m) _Pragma("unroll") for (int k = 0; k < 2; ++k) dst[m][k] = *(const LAS bf16x8*)(lds + PG8_SA(b, h) + aoff + m * 2048 + k * 1024); } while (0)
; #define PG8_LDB(dst, b, h) do { _Pragma("unroll") for (int n = 0; n < 2; ++n) _Pragma("unroll") for (int k = 0; k < 2; ++k) dst[n][k] = *(const LAS bf16x8*)(lds + PG8_SB(b, h) + boff + n * 2048 + k * 1024); } while (0)
; #define PG8_WAIT_V(n) asm volatile("s_waitcnt vmcnt(" #n ")" ::: "memory")
; #define PG8_WAIT_L(n) asm volatile("s_waitcnt lgkmcnt(" #n ")" ::: "memory")
; #define PG8_BAR __builtin_amdgcn_s_barrier()
; #define PG8_SCHED __builtin_amdgcn_sched_barrier(0)
; template <class Epi, bool ALIGN_EPI = PG8_ALIGN, bool SP2 = PG8_SP2>
; __device__ __forceinline__ void gemm_phase(LAS unsigned char* lds, const Gemm g, const StaticOrder& S, const Epi& E) {
;     ...
;         const bool has_next = S.next(ui + 1, nxt);
;         const char* nA = has_next ? (const char*)g.A + (size_t)nxt.pm * tstepA : cA; const char* nB = has_next ? (const char*)g.Bt + (size_t)nxt.pn * tstepB : cB;
;         for (int t = 0; t < nt; t += 2) {
;             const bool last = (t == nt - 2);
;             const char* a1 = cA + (size_t)(t + 1) * kstepA;
;             const char* a2 = last ? nA : cA + (size_t)(t + 2) * kstepA; const char* b2 = last ? nB : cB + (size_t)(t + 2) * kstepB;
;             const char* a3 = a2 + kstepA; const char* b3 = b2 + kstepB;
;             if constexpr (SP2) {
;             PG8_LDB(B0, 0, 0); PG8_LDB(B1, 0, 1); PG8_SCHED; PG8_LDA(At, 0, 0); PG8_STAGE(PG8_SA(1, 1), a1 + hstepA, voffA);
;             PG8_WAIT_V(8); PG8_WAIT_L(0); PG8_BAR; PG8_MMA(0, 0, At, B0); PG8_MMA(0, 1, At, B1); PG8_BAR; PG8_SCHED;
;             PG8_LDA(At, 0, 1); PG8_STAGE(PG8_SB(0, 0), b2, voffB); PG8_STAGE(PG8_SB(0, 1), b2 + hstepB, voffB); PG8_STAGE(PG8_SA(0, 0), a2, voffA);
;             PG8_WAIT_V(8); PG8_WAIT_L(0); PG8_BAR; PG8_MMA(1, 0, At, B0); PG8_MMA(1, 1, At, B1); PG8_BAR; PG8_SCHED;
.LBB0_610:
	s_ashr_i32 s13, s12, 31
	s_lshl_b64 s[14:15], s[12:13], 19
	v_readlane_b32 s16, v252, 58
	v_readlane_b32 s17, v252, 59
	s_add_u32 s14, s16, s14
	s_addc_u32 s15, s17, s15
	s_and_b64 s[16:17], s[0:1], exec
	s_cselect_b32 s13, s15, s21
	s_cselect_b32 s43, s14, s20
	s_ashr_i32 s11, s10, 31
	s_lshl_b64 s[16:17], s[10:11], 19
	s_add_u32 s16, s30, s16
	s_addc_u32 s17, s31, s17
	s_and_b64 s[24:25], s[0:1], exec
	s_cselect_b32 s11, s17, s23
	s_cselect_b32 s44, s16, s22
	s_add_u32 s20, s20, 0x40080
	s_addc_u32 s21, s21, 0
	s_add_u32 s45, s22, 0x100
	s_addc_u32 s46, s23, 0
	s_mov_b32 s47, -2
	s_branch .Lfirst_iter_u611
	.p2align 6
.LBB0_611:
	s_add_i32 s48, 0, 0x10000
	v_add_u32_e32 v0, s48, v141
	s_add_i32 s52, 0, 0x14000
	ds_read_b128 v[144:147], v0
	ds_read_b128 v[148:151], v0 offset:1024
	ds_read_b128 v[152:155], v0 offset:2048
	ds_read_b128 v[156:159], v0 offset:3072
	v_add_u32_e32 v0, s52, v141
	ds_read_b128 v[170:173], v0
	ds_read_b128 v[174:177], v0 offset:1024
	ds_read_b128 v[178:181], v0 offset:2048
	ds_read_b128 v[182:185], v0 offset:3072
	s_add_i32 m0, s34, 0xc000
	ds_read_b128 v[186:189], v142
	ds_read_b128 v[206:209], v142 offset:1024
	ds_read_b128 v[210:213], v142 offset:2048
	ds_read_b128 v[214:217], v142 offset:3072
	ds_read_b128 v[218:221], v142 offset:4096
	ds_read_b128 v[222:225], v142 offset:5120
	ds_read_b128 v[226:229], v142 offset:6144
	ds_read_b128 v[230:233], v142 offset:7168
	global_load_lds_dwordx4 v134, s[20:21]
	s_add_i32 m0, s34, 0xe000
	s_nop 0
	global_load_lds_dwordx4 v136, s[20:21]
	s_add_u32 s22, s20, 0xfffc0080
	s_addc_u32 s23, s21, -1
	s_cmp_eq_u32 s47, 12
	s_cselect_b32 s25, s13, s23
	s_cselect_b32 s24, s43, s22
	s_cselect_b32 s23, s11, s46
	s_cselect_b32 s22, s44, s45
	s_waitcnt vmcnt(8)
	s_waitcnt lgkmcnt(0)
	s_barrier
	s_setprio 1
	s_waitcnt lgkmcnt(0)
	v_mfma_f32_16x16x32_bf16 v[126:129], v[144:147], v[186:189], v[126:129]
	v_mfma_f32_16x16x32_bf16 v[118:121], v[152:155], v[186:189], v[118:121]
	v_mfma_f32_16x16x32_bf16 v[110:113], v[144:147], v[210:213], v[110:113]
	v_mfma_f32_16x16x32_bf16 v[102:105], v[152:155], v[210:213], v[102:105]
	v_mfma_f32_16x16x32_bf16 v[94:97], v[144:147], v[218:221], v[94:97]
	v_mfma_f32_16x16x32_bf16 v[86:89], v[152:155], v[218:221], v[86:89]
	v_mfma_f32_16x16x32_bf16 v[78:81], v[144:147], v[226:229], v[78:81]
	v_mfma_f32_16x16x32_bf16 v[70:73], v[152:155], v[226:229], v[70:73]
	v_mfma_f32_16x16x32_bf16 v[126:129], v[148:151], v[206:209], v[126:129]
	v_mfma_f32_16x16x32_bf16 v[118:121], v[156:159], v[206:209], v[118:121]
	v_mfma_f32_16x16x32_bf16 v[110:113], v[148:151], v[214:217], v[110:113]
	v_mfma_f32_16x16x32_bf16 v[102:105], v[156:159], v[214:217], v[102:105]
	v_mfma_f32_16x16x32_bf16 v[94:97], v[148:151], v[222:225], v[94:97]
	v_mfma_f32_16x16x32_bf16 v[86:89], v[156:159], v[222:225], v[86:89]
	v_mfma_f32_16x16x32_bf16 v[78:81], v[148:151], v[230:233], v[78:81]
	v_mfma_f32_16x16x32_bf16 v[70:73], v[156:159], v[230:233], v[70:73]
	s_setprio 0
	s_setprio 1
	v_mfma_f32_16x16x32_bf16 v[122:125], v[170:173], v[186:189], v[122:125]
	v_mfma_f32_16x16x32_bf16 v[114:117], v[178:181], v[186:189], v[114:117]
	v_mfma_f32_16x16x32_bf16 v[106:109], v[170:173], v[210:213], v[106:109]
	v_mfma_f32_16x16x32_bf16 v[98:101], v[178:181], v[210:213], v[98:101]
	v_mfma_f32_16x16x32_bf16 v[90:93], v[170:173], v[218:221], v[90:93]
	v_mfma_f32_16x16x32_bf16 v[82:85], v[178:181], v[218:221], v[82:85]
	v_mfma_f32_16x16x32_bf16 v[74:77], v[170:173], v[226:229], v[74:77]
	v_mfma_f32_16x16x32_bf16 v[66:69], v[178:181], v[226:229], v[66:69]
	v_mfma_f32_16x16x32_bf16 v[122:125], v[174:177], v[206:209], v[122:125]
	v_mfma_f32_16x16x32_bf16 v[114:117], v[182:185], v[206:209], v[114:117]
	v_mfma_f32_16x16x32_bf16 v[106:109], v[174:177], v[214:217], v[106:109]
	v_mfma_f32_16x16x32_bf16 v[98:101], v[182:185], v[214:217], v[98:101]
	v_mfma_f32_16x16x32_bf16 v[90:93], v[174:177], v[222:225], v[90:93]
	v_mfma_f32_16x16x32_bf16 v[82:85], v[182:185], v[222:225], v[82:85]
	v_mfma_f32_16x16x32_bf16 v[74:77], v[174:177], v[230:233], v[74:77]
	v_mfma_f32_16x16x32_bf16 v[66:69], v[182:185], v[230:233], v[66:69]
	s_setprio 0
	s_barrier
	s_add_i32 s48, s48, s33
	s_mov_b32 m0, s48
	ds_read_b128 v[186:189], v142 offset:16384
	ds_read_b128 v[206:209], v142 offset:17408
	ds_read_b128 v[210:213], v142 offset:18432
	ds_read_b128 v[214:217], v142 offset:19456
	ds_read_b128 v[218:221], v142 offset:20480
	ds_read_b128 v[222:225], v142 offset:21504
	ds_read_b128 v[226:229], v142 offset:22528
	ds_read_b128 v[230:233], v142 offset:23552
	global_load_lds_dwordx4 v130, s[22:23]
	s_add_i32 m0, s48, 0x2000
	s_add_u32 s48, s22, 0x40000
	s_addc_u32 s49, s23, 0
	s_add_i32 s52, s52, s33
	global_load_lds_dwordx4 v132, s[22:23]
	s_mov_b32 m0, s52
	v_lshl_add_u64 v[194:195], s[24:25], 0, v[132:133]
	global_load_lds_dwordx4 v130, s[48:49]
	s_add_i32 m0, s52, 0x2000
	s_nop 0
	global_load_lds_dwordx4 v132, s[48:49]
	v_lshl_add_u64 v[166:167], s[24:25], 0, v[130:131]
	s_mov_b32 m0, s34
	s_nop 0
	global_load_lds_dwordx4 v130, s[24:25]
	s_mov_b32 m0, s35
	s_nop 0
	global_load_lds_dwordx4 v132, s[24:25]
	s_waitcnt vmcnt(8)
	s_waitcnt lgkmcnt(0)
	s_barrier
; #define PG8_STAGE(bufoff, gbase, voff) do { _Pragma("unroll") for (int _i = 0; _i < 2; ++_i) \
;         __builtin_amdgcn_global_load_lds((const unsigned*)((const char*)(gbase) + (voff)[_i]), (LAS unsigned*)(lds + (bufoff) + ldsw + _i * 8192), 16, 0, 0); } while (0)
; #define PG8_LDA(dst, b, h) do { _Pragma("unroll") for (int m = 0; m < 4; ++m) _Pragma("unroll") for (int k = 0; k < 2; ++k) dst[m][k] = *(const LAS bf16x8*)(lds + PG8_SA(b, h) + aoff + m * 2048 + k * 1024); } while (0)
; #define PG8_LDB(dst, b, h) do { _Pragma("unroll") for (int n = 0; n < 2; ++n) _Pragma("unroll") for (int k = 0; k < 2; ++k) dst[n][k] = *(const LAS bf16x8*)(lds + PG8_SB(b, h) + boff + n * 2048 + k * 1024); } while (0)
; #define PG8_MMA(ai, bj, At, Bt) do { __builtin_amdgcn_s_setprio(1); _Pragma("unroll") for (int m = 0; m < 4; ++m) _Pragma("unroll") for (int n = 0; n < 2; ++n) _Pragma("unroll") for (int k = 0; k < 2; ++k) \
;         acc[ai][bj][m][n] = __builtin_amdgcn_mfma_f32_16x16x32_bf16(Bt[n][k], At[m][k], acc[ai][bj][m][n], 0, 0, 0); __builtin_amdgcn_s_setprio(0); } while (0)
; #define PG8_WAIT_V(n) asm volatile("s_waitcnt vmcnt(" #n ")" ::: "memory")
; #define PG8_WAIT_L(n) asm volatile("s_waitcnt lgkmcnt(" #n ")" ::: "memory")
; #define PG8_BAR __builtin_amdgcn_s_barrier()
; #define PG8_SCHED __builtin_amdgcn_sched_barrier(0)
; template <class Epi, bool ALIGN_EPI = PG8_ALIGN, bool SP2 = PG8_SP2>
; __device__ __forceinline__ void gemm_phase(LAS unsigned char* lds, const Gemm g, const StaticOrder& S, const Epi& E) {
;     ...
;             PG8_WAIT_V(8); PG8_WAIT_L(0); PG8_BAR; PG8_MMA(1, 0, At, B0); PG8_MMA(1, 1, At, B1); PG8_BAR; PG8_SCHED;
;             PG8_LDB(B0, 1, 0); PG8_LDB(B1, 1, 1); PG8_SCHED; PG8_LDA(At, 1, 0); PG8_STAGE(PG8_SA(0, 1), a2 + hstepA, voffA);
;             PG8_WAIT_V(8); PG8_WAIT_L(0); PG8_BAR; PG8_MMA(0, 0, At, B0); PG8_MMA(0, 1, At, B1); PG8_BAR; PG8_SCHED;
	s_setprio 1
	s_waitcnt lgkmcnt(0)
	v_mfma_f32_16x16x32_bf16 v[62:65], v[144:147], v[186:189], v[62:65]
	v_mfma_f32_16x16x32_bf16 v[54:57], v[152:155], v[186:189], v[54:57]
	v_mfma_f32_16x16x32_bf16 v[46:49], v[144:147], v[210:213], v[46:49]
	v_mfma_f32_16x16x32_bf16 v[38:41], v[152:155], v[210:213], v[38:41]
	v_mfma_f32_16x16x32_bf16 v[30:33], v[144:147], v[218:221], v[30:33]
	v_mfma_f32_16x16x32_bf16 v[22:25], v[152:155], v[218:221], v[22:25]
	v_mfma_f32_16x16x32_bf16 v[14:17], v[144:147], v[226:229], v[14:17]
	v_mfma_f32_16x16x32_bf16 v[6:9], v[152:155], v[226:229], v[6:9]
	v_mfma_f32_16x16x32_bf16 v[62:65], v[148:151], v[206:209], v[62:65]
	v_mfma_f32_16x16x32_bf16 v[54:57], v[156:159], v[206:209], v[54:57]
	v_mfma_f32_16x16x32_bf16 v[46:49], v[148:151], v[214:217], v[46:49]
	v_mfma_f32_16x16x32_bf16 v[38:41], v[156:159], v[214:217], v[38:41]
	v_mfma_f32_16x16x32_bf16 v[30:33], v[148:151], v[222:225], v[30:33]
	v_mfma_f32_16x16x32_bf16 v[22:25], v[156:159], v[222:225], v[22:25]
	v_mfma_f32_16x16x32_bf16 v[14:17], v[148:151], v[230:233], v[14:17]
	v_mfma_f32_16x16x32_bf16 v[6:9], v[156:159], v[230:233], v[6:9]
	s_setprio 0
	s_setprio 1
	v_mfma_f32_16x16x32_bf16 v[58:61], v[170:173], v[186:189], v[58:61]
	v_mfma_f32_16x16x32_bf16 v[50:53], v[178:181], v[186:189], v[50:53]
	v_mfma_f32_16x16x32_bf16 v[42:45], v[170:173], v[210:213], v[42:45]
	v_mfma_f32_16x16x32_bf16 v[34:37], v[178:181], v[210:213], v[34:37]
	v_mfma_f32_16x16x32_bf16 v[26:29], v[170:173], v[218:221], v[26:29]
	v_mfma_f32_16x16x32_bf16 v[18:21], v[178:181], v[218:221], v[18:21]
	v_mfma_f32_16x16x32_bf16 v[10:13], v[170:173], v[226:229], v[10:13]
	v_mfma_f32_16x16x32_bf16 v[2:5], v[178:181], v[226:229], v[2:5]
	v_mfma_f32_16x16x32_bf16 v[58:61], v[174:177], v[206:209], v[58:61]
	v_mfma_f32_16x16x32_bf16 v[50:53], v[182:185], v[206:209], v[50:53]
	v_mfma_f32_16x16x32_bf16 v[42:45], v[174:177], v[214:217], v[42:45]
	v_mfma_f32_16x16x32_bf16 v[34:37], v[182:185], v[214:217], v[34:37]
	v_mfma_f32_16x16x32_bf16 v[26:29], v[174:177], v[222:225], v[26:29]
	v_mfma_f32_16x16x32_bf16 v[18:21], v[182:185], v[222:225], v[18:21]
	v_mfma_f32_16x16x32_bf16 v[10:13], v[174:177], v[230:233], v[10:13]
	v_mfma_f32_16x16x32_bf16 v[2:5], v[182:185], v[230:233], v[2:5]
	s_setprio 0
	s_barrier
	s_add_i32 s48, 0, 0x18000
	v_add_u32_e32 v0, s48, v141
	s_add_i32 s49, 0, 0x1c000
	ds_read_b128 v[144:147], v0
	ds_read_b128 v[148:151], v0 offset:1024
	ds_read_b128 v[152:155], v0 offset:2048
	ds_read_b128 v[156:159], v0 offset:3072
	v_add_u32_e32 v0, s49, v141
	ds_read_b128 v[170:173], v0
	ds_read_b128 v[174:177], v0 offset:1024
	ds_read_b128 v[178:181], v0 offset:2048
	ds_read_b128 v[182:185], v0 offset:3072
	s_add_u32 s24, s24, 0x40000
	s_addc_u32 s25, s25, 0
	s_mov_b32 m0, s36
	ds_read_b128 v[186:189], v142 offset:32768
	ds_read_b128 v[206:209], v142 offset:33792
	ds_read_b128 v[210:213], v142 offset:34816
	ds_read_b128 v[214:217], v142 offset:35840
	ds_read_b128 v[218:221], v142 offset:36864
	ds_read_b128 v[222:225], v142 offset:37888
	ds_read_b128 v[226:229], v142 offset:38912
	ds_read_b128 v[230:233], v142 offset:39936
	global_load_lds_dwordx4 v130, s[24:25]
	s_mov_b32 m0, s37
	s_nop 0
	global_load_lds_dwordx4 v132, s[24:25]
	s_waitcnt vmcnt(8)
	s_waitcnt lgkmcnt(0)
	s_barrier
	s_setprio 1
	s_waitcnt lgkmcnt(0)
	v_mfma_f32_16x16x32_bf16 v[126:129], v[144:147], v[186:189], v[126:129]
	v_mfma_f32_16x16x32_bf16 v[118:121], v[152:155], v[186:189], v[118:121]
	v_mfma_f32_16x16x32_bf16 v[110:113], v[144:147], v[210:213], v[110:113]
	v_mfma_f32_16x16x32_bf16 v[102:105], v[152:155], v[210:213], v[102:105]
	v_mfma_f32_16x16x32_bf16 v[94:97], v[144:147], v[218:221], v[94:97]
	v_mfma_f32_16x16x32_bf16 v[86:89], v[152:155], v[218:221], v[86:89]
	v_mfma_f32_16x16x32_bf16 v[78:81], v[144:147], v[226:229], v[78:81]
	v_mfma_f32_16x16x32_bf16 v[70:73], v[152:155], v[226:229], v[70:73]
	v_mfma_f32_16x16x32_bf16 v[126:129], v[148:151], v[206:209], v[126:129]
	v_mfma_f32_16x16x32_bf16 v[118:121], v[156:159], v[206:209], v[118:121]
	v_mfma_f32_16x16x32_bf16 v[110:113], v[148:151], v[214:217], v[110:113]
	v_mfma_f32_16x16x32_bf16 v[102:105], v[156:159], v[214:217], v[102:105]
	v_mfma_f32_16x16x32_bf16 v[94:97], v[148:151], v[222:225], v[94:97]
	v_mfma_f32_16x16x32_bf16 v[86:89], v[156:159], v[222:225], v[86:89]
	v_mfma_f32_16x16x32_bf16 v[78:81], v[148:151], v[230:233], v[78:81]
	v_mfma_f32_16x16x32_bf16 v[70:73], v[156:159], v[230:233], v[70:73]
	s_setprio 0
	s_setprio 1
	v_mfma_f32_16x16x32_bf16 v[122:125], v[170:173], v[186:189], v[122:125]
	v_mfma_f32_16x16x32_bf16 v[114:117], v[178:181], v[186:189], v[114:117]
	v_mfma_f32_16x16x32_bf16 v[106:109], v[170:173], v[210:213], v[106:109]
	v_mfma_f32_16x16x32_bf16 v[98:101], v[178:181], v[210:213], v[98:101]
	v_mfma_f32_16x16x32_bf16 v[90:93], v[170:173], v[218:221], v[90:93]
	v_mfma_f32_16x16x32_bf16 v[82:85], v[178:181], v[218:221], v[82:85]
	v_mfma_f32_16x16x32_bf16 v[74:77], v[170:173], v[226:229], v[74:77]
	v_mfma_f32_16x16x32_bf16 v[66:69], v[178:181], v[226:229], v[66:69]
	v_mfma_f32_16x16x32_bf16 v[122:125], v[174:177], v[206:209], v[122:125]
	v_mfma_f32_16x16x32_bf16 v[114:117], v[182:185], v[206:209], v[114:117]
	v_mfma_f32_16x16x32_bf16 v[106:109], v[174:177], v[214:217], v[106:109]
	v_mfma_f32_16x16x32_bf16 v[98:101], v[182:185], v[214:217], v[98:101]
	v_mfma_f32_16x16x32_bf16 v[90:93], v[174:177], v[222:225], v[90:93]
	v_mfma_f32_16x16x32_bf16 v[82:85], v[182:185], v[222:225], v[82:85]
	v_mfma_f32_16x16x32_bf16 v[74:77], v[174:177], v[230:233], v[74:77]
	v_mfma_f32_16x16x32_bf16 v[66:69], v[182:185], v[230:233], v[66:69]
	s_setprio 0
	s_barrier
; #define PG8_STAGE(bufoff, gbase, voff) do { _Pragma("unroll") for (int _i = 0; _i < 2; ++_i) \
;         __builtin_amdgcn_global_load_lds((const unsigned*)((const char*)(gbase) + (voff)[_i]), (LAS unsigned*)(lds + (bufoff) + ldsw + _i * 8192), 16, 0, 0); } while (0)
; #define PG8_LDA(dst, b, h) do { _Pragma("unroll") for (int m = 0; m < 4; ++m) _Pragma("unroll") for (int k = 0; k < 2; ++k) dst[m][k] = *(const LAS bf16x8*)(lds + PG8_SA(b, h) + aoff + m * 2048 + k * 1024); } while (0)
; #define PG8_LDB(dst, b, h) do { _Pragma("unroll") for (int n = 0; n < 2; ++n) _Pragma("unroll") for (int k = 0; k < 2; ++k) dst[n][k] = *(const LAS bf16x8*)(lds + PG8_SB(b, h) + boff + n * 2048 + k * 1024); } while (0)
; #define PG8_MMA(ai, bj, At, Bt) do { __builtin_amdgcn_s_setprio(1); _Pragma("unroll") for (int m = 0; m < 4; ++m) _Pragma("unroll") for (int n = 0; n < 2; ++n) _Pragma("unroll") for (int k = 0; k < 2; ++k) \
;         acc[ai][bj][m][n] = __builtin_amdgcn_mfma_f32_16x16x32_bf16(Bt[n][k], At[m][k], acc[ai][bj][m][n], 0, 0, 0); __builtin_amdgcn_s_setprio(0); } while (0)
; #define PG8_WAIT_V(n) asm volatile("s_waitcnt vmcnt(" #n ")" ::: "memory")
; #define PG8_WAIT_L(n) asm volatile("s_waitcnt lgkmcnt(" #n ")" ::: "memory")
; #define PG8_BAR __builtin_amdgcn_s_barrier()
; #define PG8_SCHED __builtin_amdgcn_sched_barrier(0)
; template <class Epi, bool ALIGN_EPI = PG8_ALIGN, bool SP2 = PG8_SP2>
; __device__ __forceinline__ void gemm_phase(LAS unsigned char* lds, const Gemm g, const StaticOrder& S, const Epi& E) {
;     ...
;             PG8_LDB(B0, 1, 0); PG8_LDB(B1, 1, 1); PG8_SCHED; PG8_LDA(At, 1, 0); PG8_STAGE(PG8_SA(0, 1), a2 + hstepA, voffA);
;             PG8_WAIT_V(8); PG8_WAIT_L(0); PG8_BAR; PG8_MMA(0, 0, At, B0); PG8_MMA(0, 1, At, B1); PG8_BAR; PG8_SCHED;
;             PG8_LDA(At, 1, 1); PG8_STAGE(PG8_SB(1, 0), b3, voffB); PG8_STAGE(PG8_SB(1, 1), b3 + hstepB, voffB); PG8_STAGE(PG8_SA(1, 0), a3, voffA);
;             PG8_WAIT_V(8); PG8_WAIT_L(0); PG8_BAR; PG8_MMA(1, 0, At, B0); PG8_MMA(1, 1, At, B1); PG8_BAR; PG8_SCHED;
	s_add_i32 s24, s48, s33
	s_add_u32 vcc_lo, s22, s50
	s_addc_u32 vcc_hi, s23, s51
	s_mov_b32 m0, s24
	ds_read_b128 v[186:189], v142 offset:49152
	ds_read_b128 v[206:209], v142 offset:50176
	ds_read_b128 v[210:213], v142 offset:51200
	ds_read_b128 v[214:217], v142 offset:52224
	ds_read_b128 v[218:221], v142 offset:53248
	ds_read_b128 v[222:225], v142 offset:54272
	ds_read_b128 v[226:229], v142 offset:55296
	ds_read_b128 v[230:233], v142 offset:56320
	global_load_lds_dwordx4 v130, vcc
	s_add_i32 m0, s24, 0x2000
	s_add_u32 s22, s22, 0x40080
	s_addc_u32 s23, s23, 0
	s_add_i32 s24, s49, s33
	global_load_lds_dwordx4 v132, vcc
	s_mov_b32 m0, s24
	s_nop 0
	global_load_lds_dwordx4 v130, s[22:23]
	s_add_i32 m0, s24, 0x2000
	s_nop 0
	global_load_lds_dwordx4 v132, s[22:23]
	v_lshl_add_u64 v[160:161], v[166:167], 0, s[50:51]
	s_mov_b32 m0, s40
	s_nop 0
	global_load_lds_dwordx4 v[160:161], off
	v_lshl_add_u64 v[160:161], v[194:195], 0, s[50:51]
	s_mov_b32 m0, s41
	s_nop 0
	global_load_lds_dwordx4 v[160:161], off
	s_waitcnt vmcnt(8)
	s_waitcnt lgkmcnt(0)
	s_barrier
	s_setprio 1
	s_waitcnt lgkmcnt(0)
	v_mfma_f32_16x16x32_bf16 v[62:65], v[144:147], v[186:189], v[62:65]
	v_mfma_f32_16x16x32_bf16 v[54:57], v[152:155], v[186:189], v[54:57]
	v_mfma_f32_16x16x32_bf16 v[46:49], v[144:147], v[210:213], v[46:49]
	v_mfma_f32_16x16x32_bf16 v[38:41], v[152:155], v[210:213], v[38:41]
	v_mfma_f32_16x16x32_bf16 v[30:33], v[144:147], v[218:221], v[30:33]
	v_mfma_f32_16x16x32_bf16 v[22:25], v[152:155], v[218:221], v[22:25]
	v_mfma_f32_16x16x32_bf16 v[14:17], v[144:147], v[226:229], v[14:17]
	v_mfma_f32_16x16x32_bf16 v[6:9], v[152:155], v[226:229], v[6:9]
	v_mfma_f32_16x16x32_bf16 v[62:65], v[148:151], v[206:209], v[62:65]
	v_mfma_f32_16x16x32_bf16 v[54:57], v[156:159], v[206:209], v[54:57]
	v_mfma_f32_16x16x32_bf16 v[46:49], v[148:151], v[214:217], v[46:49]
	v_mfma_f32_16x16x32_bf16 v[38:41], v[156:159], v[214:217], v[38:41]
	v_mfma_f32_16x16x32_bf16 v[30:33], v[148:151], v[222:225], v[30:33]
	v_mfma_f32_16x16x32_bf16 v[22:25], v[156:159], v[222:225], v[22:25]
	v_mfma_f32_16x16x32_bf16 v[14:17], v[148:151], v[230:233], v[14:17]
	v_mfma_f32_16x16x32_bf16 v[6:9], v[156:159], v[230:233], v[6:9]
	s_setprio 0
	s_setprio 1
	v_mfma_f32_16x16x32_bf16 v[58:61], v[170:173], v[186:189], v[58:61]
	v_mfma_f32_16x16x32_bf16 v[50:53], v[178:181], v[186:189], v[50:53]
	v_mfma_f32_16x16x32_bf16 v[42:45], v[170:173], v[210:213], v[42:45]
	v_mfma_f32_16x16x32_bf16 v[34:37], v[178:181], v[210:213], v[34:37]
	v_mfma_f32_16x16x32_bf16 v[26:29], v[170:173], v[218:221], v[26:29]
	v_mfma_f32_16x16x32_bf16 v[18:21], v[178:181], v[218:221], v[18:21]
	v_mfma_f32_16x16x32_bf16 v[10:13], v[170:173], v[226:229], v[10:13]
	v_mfma_f32_16x16x32_bf16 v[2:5], v[178:181], v[226:229], v[2:5]
	v_mfma_f32_16x16x32_bf16 v[58:61], v[174:177], v[206:209], v[58:61]
	v_mfma_f32_16x16x32_bf16 v[50:53], v[182:185], v[206:209], v[50:53]
	v_mfma_f32_16x16x32_bf16 v[42:45], v[174:177], v[214:217], v[42:45]
	v_mfma_f32_16x16x32_bf16 v[34:37], v[182:185], v[214:217], v[34:37]
	v_mfma_f32_16x16x32_bf16 v[26:29], v[174:177], v[222:225], v[26:29]
	v_mfma_f32_16x16x32_bf16 v[18:21], v[182:185], v[222:225], v[18:21]
	v_mfma_f32_16x16x32_bf16 v[10:13], v[174:177], v[230:233], v[10:13]
	v_mfma_f32_16x16x32_bf16 v[2:5], v[182:185], v[230:233], v[2:5]
	s_setprio 0
	s_barrier
	s_add_i32 s47, s47, 2
	s_add_u32 s20, s20, 0x100
	s_addc_u32 s21, s21, 0
	s_add_u32 s45, s45, 0x100
	s_addc_u32 s46, s46, 0
	s_cmp_gt_u32 s47, 13
	s_cbranch_scc0 .LBB0_611
	s_and_b64 vcc, exec, s[8:9]
	s_cbranch_vccz .LBB0_614
	s_barrier

; #define PG8_STAGE(bufoff, gbase, voff) do { _Pragma("unroll") for (int _i = 0; _i < 2; ++_i) \
;         __builtin_amdgcn_global_load_lds((const unsigned*)((const char*)(gbase) + (voff)[_i]), (LAS unsigned*)(lds + (bufoff) + ldsw + _i * 8192), 16, 0, 0); } while (0)
; #define PG8_LDA(dst, b, h) do { _Pragma("unroll") for (int m = 0; m < 4; ++m) _Pragma("unroll") for (int k = 0; k < 2; ++k) dst[m][k] = *(const LAS bf16x8*)(lds + PG8_SA(b, h) + aoff + m * 2048 + k * 1024); } while (0)
; #define PG8_LDB(dst, b, h) do { _Pragma("unroll") for (int n = 0; n < 2; ++n) _Pragma("unroll") for (int k = 0; k < 2; ++k) dst[n][k] = *(const LAS bf16x8*)(lds + PG8_SB(b, h) + boff + n * 2048 + k * 1024); } while (0)
; #define PG8_MMA(ai, bj, At, Bt) do { __builtin_amdgcn_s_setprio(1); _Pragma("unroll") for (int m = 0; m < 4; ++m) _Pragma("unroll") for (int n = 0; n < 2; ++n) _Pragma("unroll") for (int k = 0; k < 2; ++k) \
;         acc[ai][bj][m][n] = __builtin_amdgcn_mfma_f32_16x16x32_bf16(Bt[n][k], At[m][k], acc[ai][bj][m][n], 0, 0, 0); __builtin_amdgcn_s_setprio(0); } while (0)
; #define PG8_WAIT_V(n) asm volatile("s_waitcnt vmcnt(" #n ")" ::: "memory")
; #define PG8_WAIT_L(n) asm volatile("s_waitcnt lgkmcnt(" #n ")" ::: "memory")
; #define PG8_BAR __builtin_amdgcn_s_barrier()
; #define PG8_SCHED __builtin_amdgcn_sched_barrier(0)
; template <class Epi, bool ALIGN_EPI = PG8_ALIGN, bool SP2 = PG8_SP2>
; __device__ __forceinline__ void gemm_phase(LAS unsigned char* lds, const Gemm g, const StaticOrder& S, const Epi& E) {
;     ...
;             PG8_LDB(B0, 0, 0); PG8_LDB(B1, 0, 1); PG8_SCHED; PG8_LDA(At, 0, 0); PG8_STAGE(PG8_SA(1, 1), a1 + hstepA, voffA);
;             PG8_WAIT_V(8); PG8_WAIT_L(0); PG8_BAR; PG8_MMA(0, 0, At, B0); PG8_MMA(0, 1, At, B1); PG8_BAR; PG8_SCHED;
;             PG8_LDA(At, 0, 1); PG8_STAGE(PG8_SB(0, 0), b2, voffB); PG8_STAGE(PG8_SB(0, 1), b2 + hstepB, voffB); PG8_STAGE(PG8_SA(0, 0), a2, voffA);
;             PG8_WAIT_V(8); PG8_WAIT_L(0); PG8_BAR; PG8_MMA(1, 0, At, B0); PG8_MMA(1, 1, At, B1); PG8_BAR; PG8_SCHED;
.Lfirst_iter_u611:
	s_add_i32 s48, 0, 0x10000
	v_add_u32_e32 v0, s48, v141
	s_add_i32 s52, 0, 0x14000
	ds_read_b128 v[144:147], v0
	ds_read_b128 v[148:151], v0 offset:1024
	ds_read_b128 v[152:155], v0 offset:2048
	ds_read_b128 v[156:159], v0 offset:3072
	v_add_u32_e32 v0, s52, v141
	ds_read_b128 v[170:173], v0
	ds_read_b128 v[174:177], v0 offset:1024
	ds_read_b128 v[178:181], v0 offset:2048
	ds_read_b128 v[182:185], v0 offset:3072
	s_add_i32 m0, s34, 0xc000
	ds_read_b128 v[186:189], v142
	ds_read_b128 v[206:209], v142 offset:1024
	ds_read_b128 v[210:213], v142 offset:2048
	ds_read_b128 v[214:217], v142 offset:3072
	ds_read_b128 v[218:221], v142 offset:4096
	ds_read_b128 v[222:225], v142 offset:5120
	ds_read_b128 v[226:229], v142 offset:6144
	ds_read_b128 v[230:233], v142 offset:7168
	global_load_lds_dwordx4 v134, s[20:21]
	s_add_i32 m0, s34, 0xe000
	s_nop 0
	global_load_lds_dwordx4 v136, s[20:21]
	s_add_u32 s22, s20, 0xfffc0080
	s_addc_u32 s23, s21, -1
	s_cmp_eq_u32 s47, 12
	s_cselect_b32 s25, s13, s23
	s_cselect_b32 s24, s43, s22
	s_cselect_b32 s23, s11, s46
	s_cselect_b32 s22, s44, s45
	s_waitcnt vmcnt(8)
	s_waitcnt lgkmcnt(0)
	s_barrier
	s_setprio 1
	s_waitcnt lgkmcnt(0)
	v_mfma_f32_16x16x32_bf16 v[126:129], v[144:147], v[186:189], 0
	v_mfma_f32_16x16x32_bf16 v[118:121], v[152:155], v[186:189], 0
	v_mfma_f32_16x16x32_bf16 v[110:113], v[144:147], v[210:213], 0
	v_mfma_f32_16x16x32_bf16 v[102:105], v[152:155], v[210:213], 0
	v_mfma_f32_16x16x32_bf16 v[94:97], v[144:147], v[218:221], 0
	v_mfma_f32_16x16x32_bf16 v[86:89], v[152:155], v[218:221], 0
	v_mfma_f32_16x16x32_bf16 v[78:81], v[144:147], v[226:229], 0
	v_mfma_f32_16x16x32_bf16 v[70:73], v[152:155], v[226:229], 0
	v_mfma_f32_16x16x32_bf16 v[126:129], v[148:151], v[206:209], v[126:129]
	v_mfma_f32_16x16x32_bf16 v[118:121], v[156:159], v[206:209], v[118:121]
	v_mfma_f32_16x16x32_bf16 v[110:113], v[148:151], v[214:217], v[110:113]
	v_mfma_f32_16x16x32_bf16 v[102:105], v[156:159], v[214:217], v[102:105]
	v_mfma_f32_16x16x32_bf16 v[94:97], v[148:151], v[222:225], v[94:97]
	v_mfma_f32_16x16x32_bf16 v[86:89], v[156:159], v[222:225], v[86:89]
	v_mfma_f32_16x16x32_bf16 v[78:81], v[148:151], v[230:233], v[78:81]
	v_mfma_f32_16x16x32_bf16 v[70:73], v[156:159], v[230:233], v[70:73]
	s_setprio 0
	s_setprio 1
	v_mfma_f32_16x16x32_bf16 v[122:125], v[170:173], v[186:189], 0
	v_mfma_f32_16x16x32_bf16 v[114:117], v[178:181], v[186:189], 0
	v_mfma_f32_16x16x32_bf16 v[106:109], v[170:173], v[210:213], 0
	v_mfma_f32_16x16x32_bf16 v[98:101], v[178:181], v[210:213], 0
	v_mfma_f32_16x16x32_bf16 v[90:93], v[170:173], v[218:221], 0
	v_mfma_f32_16x16x32_bf16 v[82:85], v[178:181], v[218:221], 0
	v_mfma_f32_16x16x32_bf16 v[74:77], v[170:173], v[226:229], 0
	v_mfma_f32_16x16x32_bf16 v[66:69], v[178:181], v[226:229], 0
	v_mfma_f32_16x16x32_bf16 v[122:125], v[174:177], v[206:209], v[122:125]
	v_mfma_f32_16x16x32_bf16 v[114:117], v[182:185], v[206:209], v[114:117]
	v_mfma_f32_16x16x32_bf16 v[106:109], v[174:177], v[214:217], v[106:109]
	v_mfma_f32_16x16x32_bf16 v[98:101], v[182:185], v[214:217], v[98:101]
	v_mfma_f32_16x16x32_bf16 v[90:93], v[174:177], v[222:225], v[90:93]
	v_mfma_f32_16x16x32_bf16 v[82:85], v[182:185], v[222:225], v[82:85]
	v_mfma_f32_16x16x32_bf16 v[74:77], v[174:177], v[230:233], v[74:77]
	v_mfma_f32_16x16x32_bf16 v[66:69], v[182:185], v[230:233], v[66:69]
	s_setprio 0
	s_barrier
	s_add_i32 s48, s48, s33
	s_mov_b32 m0, s48
	ds_read_b128 v[186:189], v142 offset:16384
	ds_read_b128 v[206:209], v142 offset:17408
	ds_read_b128 v[210:213], v142 offset:18432
	ds_read_b128 v[214:217], v142 offset:19456
	ds_read_b128 v[218:221], v142 offset:20480
	ds_read_b128 v[222:225], v142 offset:21504
	ds_read_b128 v[226:229], v142 offset:22528
	ds_read_b128 v[230:233], v142 offset:23552
	global_load_lds_dwordx4 v130, s[22:23]
	s_add_i32 m0, s48, 0x2000
	s_add_u32 s48, s22, 0x40000
	s_addc_u32 s49, s23, 0
	s_add_i32 s52, s52, s33
	global_load_lds_dwordx4 v132, s[22:23]
	s_mov_b32 m0, s52
	v_lshl_add_u64 v[194:195], s[24:25], 0, v[132:133]
	global_load_lds_dwordx4 v130, s[48:49]
	s_add_i32 m0, s52, 0x2000
	s_nop 0
	global_load_lds_dwordx4 v132, s[48:49]
	v_lshl_add_u64 v[166:167], s[24:25], 0, v[130:131]
	s_mov_b32 m0, s34
	s_nop 0
	global_load_lds_dwordx4 v130, s[24:25]
	s_mov_b32 m0, s35
	s_nop 0
	global_load_lds_dwordx4 v132, s[24:25]
	s_waitcnt vmcnt(8)
	s_waitcnt lgkmcnt(0)
	s_barrier
	s_setprio 1
	s_waitcnt lgkmcnt(0)
	v_mfma_f32_16x16x32_bf16 v[62:65], v[144:147], v[186:189], 0
	v_mfma_f32_16x16x32_bf16 v[54:57], v[152:155], v[186:189], 0
	v_mfma_f32_16x16x32_bf16 v[46:49], v[144:147], v[210:213], 0
	v_mfma_f32_16x16x32_bf16 v[38:41], v[152:155], v[210:213], 0
	v_mfma_f32_16x16x32_bf16 v[30:33], v[144:147], v[218:221], 0
	v_mfma_f32_16x16x32_bf16 v[22:25], v[152:155], v[218:221], 0
	v_mfma_f32_16x16x32_bf16 v[14:17], v[144:147], v[226:229], 0
	v_mfma_f32_16x16x32_bf16 v[6:9], v[152:155], v[226:229], 0
	v_mfma_f32_16x16x32_bf16 v[62:65], v[148:151], v[206:209], v[62:65]
	v_mfma_f32_16x16x32_bf16 v[54:57], v[156:159], v[206:209], v[54:57]
	v_mfma_f32_16x16x32_bf16 v[46:49], v[148:151], v[214:217], v[46:49]
	v_mfma_f32_16x16x32_bf16 v[38:41], v[156:159], v[214:217], v[38:41]
	v_mfma_f32_16x16x32_bf16 v[30:33], v[148:151], v[222:225], v[30:33]
	v_mfma_f32_16x16x32_bf16 v[22:25], v[156:159], v[222:225], v[22:25]
	v_mfma_f32_16x16x32_bf16 v[14:17], v[148:151], v[230:233], v[14:17]
	v_mfma_f32_16x16x32_bf16 v[6:9], v[156:159], v[230:233], v[6:9]
	s_setprio 0
	s_setprio 1
	v_mfma_f32_16x16x32_bf16 v[58:61], v[170:173], v[186:189], 0
	v_mfma_f32_16x16x32_bf16 v[50:53], v[178:181], v[186:189], 0
	v_mfma_f32_16x16x32_bf16 v[42:45], v[170:173], v[210:213], 0
	v_mfma_f32_16x16x32_bf16 v[34:37], v[178:181], v[210:213], 0
	v_mfma_f32_16x16x32_bf16 v[26:29], v[170:173], v[218:221], 0
	v_mfma_f32_16x16x32_bf16 v[18:21], v[178:181], v[218:221], 0
	v_mfma_f32_16x16x32_bf16 v[10:13], v[170:173], v[226:229], 0
	v_mfma_f32_16x16x32_bf16 v[2:5], v[178:181], v[226:229], 0
	v_mfma_f32_16x16x32_bf16 v[58:61], v[174:177], v[206:209], v[58:61]
	v_mfma_f32_16x16x32_bf16 v[50:53], v[182:185], v[206:209], v[50:53]
	v_mfma_f32_16x16x32_bf16 v[42:45], v[174:177], v[214:217], v[42:45]
	v_mfma_f32_16x16x32_bf16 v[34:37], v[182:185], v[214:217], v[34:37]
	v_mfma_f32_16x16x32_bf16 v[26:29], v[174:177], v[222:225], v[26:29]
	v_mfma_f32_16x16x32_bf16 v[18:21], v[182:185], v[222:225], v[18:21]
	v_mfma_f32_16x16x32_bf16 v[10:13], v[174:177], v[230:233], v[10:13]
	v_mfma_f32_16x16x32_bf16 v[2:5], v[182:185], v[230:233], v[2:5]
	s_setprio 0
	s_barrier
; #define PG8_STAGE(bufoff, gbase, voff) do { _Pragma("unroll") for (int _i = 0; _i < 2; ++_i) \
;         __builtin_amdgcn_global_load_lds((const unsigned*)((const char*)(gbase) + (voff)[_i]), (LAS unsigned*)(lds + (bufoff) + ldsw + _i * 8192), 16, 0, 0); } while (0)
; #define PG8_LDA(dst, b, h) do { _Pragma("unroll") for (int m = 0; m < 4; ++m) _Pragma("unroll") for (int k = 0; k < 2; ++k) dst[m][k] = *(const LAS bf16x8*)(lds + PG8_SA(b, h) + aoff + m * 2048 + k * 1024); } while (0)
; #define PG8_LDB(dst, b, h) do { _Pragma("unroll") for (int n = 0; n < 2; ++n) _Pragma("unroll") for (int k = 0; k < 2; ++k) dst[n][k] = *(const LAS bf16x8*)(lds + PG8_SB(b, h) + boff + n * 2048 + k * 1024); } while (0)
; #define PG8_MMA(ai, bj, At, Bt) do { __builtin_amdgcn_s_setprio(1); _Pragma("unroll") for (int m = 0; m < 4; ++m) _Pragma("unroll") for (int n = 0; n < 2; ++n) _Pragma("unroll") for (int k = 0; k < 2; ++k) \
;         acc[ai][bj][m][n] = __builtin_amdgcn_mfma_f32_16x16x32_bf16(Bt[n][k], At[m][k], acc[ai][bj][m][n], 0, 0, 0); __builtin_amdgcn_s_setprio(0); } while (0)
; #define PG8_WAIT_V(n) asm volatile("s_waitcnt vmcnt(" #n ")" ::: "memory")
; #define PG8_WAIT_L(n) asm volatile("s_waitcnt lgkmcnt(" #n ")" ::: "memory")
; #define PG8_BAR __builtin_amdgcn_s_barrier()
; #define PG8_SCHED __builtin_amdgcn_sched_barrier(0)
; template <class Epi, bool ALIGN_EPI = PG8_ALIGN, bool SP2 = PG8_SP2>
; __device__ __forceinline__ void gemm_phase(LAS unsigned char* lds, const Gemm g, const StaticOrder& S, const Epi& E) {
;     ...
;             PG8_LDB(B0, 1, 0); PG8_LDB(B1, 1, 1); PG8_SCHED; PG8_LDA(At, 1, 0); PG8_STAGE(PG8_SA(0, 1), a2 + hstepA, voffA);
;             PG8_WAIT_V(8); PG8_WAIT_L(0); PG8_BAR; PG8_MMA(0, 0, At, B0); PG8_MMA(0, 1, At, B1); PG8_BAR; PG8_SCHED;
;             PG8_LDA(At, 1, 1); PG8_STAGE(PG8_SB(1, 0), b3, voffB); PG8_STAGE(PG8_SB(1, 1), b3 + hstepB, voffB); PG8_STAGE(PG8_SA(1, 0), a3, voffA);
;             PG8_WAIT_V(8); PG8_WAIT_L(0); PG8_BAR; PG8_MMA(1, 0, At, B0); PG8_MMA(1, 1, At, B1); PG8_BAR; PG8_SCHED;
	s_add_i32 s48, 0, 0x18000
	v_add_u32_e32 v0, s48, v141
	s_add_i32 s49, 0, 0x1c000
	ds_read_b128 v[144:147], v0
	ds_read_b128 v[148:151], v0 offset:1024
	ds_read_b128 v[152:155], v0 offset:2048
	ds_read_b128 v[156:159], v0 offset:3072
	v_add_u32_e32 v0, s49, v141
	ds_read_b128 v[170:173], v0
	ds_read_b128 v[174:177], v0 offset:1024
	ds_read_b128 v[178:181], v0 offset:2048
	ds_read_b128 v[182:185], v0 offset:3072
	s_add_u32 s24, s24, 0x40000
	s_addc_u32 s25, s25, 0
	s_mov_b32 m0, s36
	ds_read_b128 v[186:189], v142 offset:32768
	ds_read_b128 v[206:209], v142 offset:33792
	ds_read_b128 v[210:213], v142 offset:34816
	ds_read_b128 v[214:217], v142 offset:35840
	ds_read_b128 v[218:221], v142 offset:36864
	ds_read_b128 v[222:225], v142 offset:37888
	ds_read_b128 v[226:229], v142 offset:38912
	ds_read_b128 v[230:233], v142 offset:39936
	global_load_lds_dwordx4 v130, s[24:25]
	s_mov_b32 m0, s37
	s_nop 0
	global_load_lds_dwordx4 v132, s[24:25]
	s_waitcnt vmcnt(8)
	s_waitcnt lgkmcnt(0)
	s_barrier
	s_setprio 1
	s_waitcnt lgkmcnt(0)
	v_mfma_f32_16x16x32_bf16 v[126:129], v[144:147], v[186:189], v[126:129]
	v_mfma_f32_16x16x32_bf16 v[118:121], v[152:155], v[186:189], v[118:121]
	v_mfma_f32_16x16x32_bf16 v[110:113], v[144:147], v[210:213], v[110:113]
	v_mfma_f32_16x16x32_bf16 v[102:105], v[152:155], v[210:213], v[102:105]
	v_mfma_f32_16x16x32_bf16 v[94:97], v[144:147], v[218:221], v[94:97]
	v_mfma_f32_16x16x32_bf16 v[86:89], v[152:155], v[218:221], v[86:89]
	v_mfma_f32_16x16x32_bf16 v[78:81], v[144:147], v[226:229], v[78:81]
	v_mfma_f32_16x16x32_bf16 v[70:73], v[152:155], v[226:229], v[70:73]
	v_mfma_f32_16x16x32_bf16 v[126:129], v[148:151], v[206:209], v[126:129]
	v_mfma_f32_16x16x32_bf16 v[118:121], v[156:159], v[206:209], v[118:121]
	v_mfma_f32_16x16x32_bf16 v[110:113], v[148:151], v[214:217], v[110:113]
	v_mfma_f32_16x16x32_bf16 v[102:105], v[156:159], v[214:217], v[102:105]
	v_mfma_f32_16x16x32_bf16 v[94:97], v[148:151], v[222:225], v[94:97]
	v_mfma_f32_16x16x32_bf16 v[86:89], v[156:159], v[222:225], v[86:89]
	v_mfma_f32_16x16x32_bf16 v[78:81], v[148:151], v[230:233], v[78:81]
	v_mfma_f32_16x16x32_bf16 v[70:73], v[156:159], v[230:233], v[70:73]
	s_setprio 0
	s_setprio 1
	v_mfma_f32_16x16x32_bf16 v[122:125], v[170:173], v[186:189], v[122:125]
	v_mfma_f32_16x16x32_bf16 v[114:117], v[178:181], v[186:189], v[114:117]
	v_mfma_f32_16x16x32_bf16 v[106:109], v[170:173], v[210:213], v[106:109]
	v_mfma_f32_16x16x32_bf16 v[98:101], v[178:181], v[210:213], v[98:101]
	v_mfma_f32_16x16x32_bf16 v[90:93], v[170:173], v[218:221], v[90:93]
	v_mfma_f32_16x16x32_bf16 v[82:85], v[178:181], v[218:221], v[82:85]
	v_mfma_f32_16x16x32_bf16 v[74:77], v[170:173], v[226:229], v[74:77]
	v_mfma_f32_16x16x32_bf16 v[66:69], v[178:181], v[226:229], v[66:69]
	v_mfma_f32_16x16x32_bf16 v[122:125], v[174:177], v[206:209], v[122:125]
	v_mfma_f32_16x16x32_bf16 v[114:117], v[182:185], v[206:209], v[114:117]
	v_mfma_f32_16x16x32_bf16 v[106:109], v[174:177], v[214:217], v[106:109]
	v_mfma_f32_16x16x32_bf16 v[98:101], v[182:185], v[214:217], v[98:101]
	v_mfma_f32_16x16x32_bf16 v[90:93], v[174:177], v[222:225], v[90:93]
	v_mfma_f32_16x16x32_bf16 v[82:85], v[182:185], v[222:225], v[82:85]
	v_mfma_f32_16x16x32_bf16 v[74:77], v[174:177], v[230:233], v[74:77]
	v_mfma_f32_16x16x32_bf16 v[66:69], v[182:185], v[230:233], v[66:69]
	s_setprio 0
	s_barrier
	s_add_i32 s24, s48, s33
	s_add_u32 vcc_lo, s22, s50
	s_addc_u32 vcc_hi, s23, s51
	s_mov_b32 m0, s24
	ds_read_b128 v[186:189], v142 offset:49152
	ds_read_b128 v[206:209], v142 offset:50176
	ds_read_b128 v[210:213], v142 offset:51200
	ds_read_b128 v[214:217], v142 offset:52224
	ds_read_b128 v[218:221], v142 offset:53248
	ds_read_b128 v[222:225], v142 offset:54272
	ds_read_b128 v[226:229], v142 offset:55296
	ds_read_b128 v[230:233], v142 offset:56320
	global_load_lds_dwordx4 v130, vcc
	s_add_i32 m0, s24, 0x2000
	s_add_u32 s22, s22, 0x40080
	s_addc_u32 s23, s23, 0
	s_add_i32 s24, s49, s33
	global_load_lds_dwordx4 v132, vcc
	s_mov_b32 m0, s24
	s_nop 0
	global_load_lds_dwordx4 v130, s[22:23]
	s_add_i32 m0, s24, 0x2000
	s_nop 0
	global_load_lds_dwordx4 v132, s[22:23]
	v_lshl_add_u64 v[160:161], v[166:167], 0, s[50:51]
	s_mov_b32 m0, s40
	s_nop 0
	global_load_lds_dwordx4 v[160:161], off
	v_lshl_add_u64 v[160:161], v[194:195], 0, s[50:51]
	s_mov_b32 m0, s41
	s_nop 0
	global_load_lds_dwordx4 v[160:161], off
	s_waitcnt vmcnt(8)
	s_waitcnt lgkmcnt(0)
	s_barrier
	s_setprio 1
	s_waitcnt lgkmcnt(0)
	v_mfma_f32_16x16x32_bf16 v[62:65], v[144:147], v[186:189], v[62:65]
	v_mfma_f32_16x16x32_bf16 v[54:57], v[152:155], v[186:189], v[54:57]
	v_mfma_f32_16x16x32_bf16 v[46:49], v[144:147], v[210:213], v[46:49]
	v_mfma_f32_16x16x32_bf16 v[38:41], v[152:155], v[210:213], v[38:41]
	v_mfma_f32_16x16x32_bf16 v[30:33], v[144:147], v[218:221], v[30:33]
	v_mfma_f32_16x16x32_bf16 v[22:25], v[152:155], v[218:221], v[22:25]
	v_mfma_f32_16x16x32_bf16 v[14:17], v[144:147], v[226:229], v[14:17]
	v_mfma_f32_16x16x32_bf16 v[6:9], v[152:155], v[226:229], v[6:9]
	v_mfma_f32_16x16x32_bf16 v[62:65], v[148:151], v[206:209], v[62:65]
	v_mfma_f32_16x16x32_bf16 v[54:57], v[156:159], v[206:209], v[54:57]
	v_mfma_f32_16x16x32_bf16 v[46:49], v[148:151], v[214:217], v[46:49]
	v_mfma_f32_16x16x32_bf16 v[38:41], v[156:159], v[214:217], v[38:41]
	v_mfma_f32_16x16x32_bf16 v[30:33], v[148:151], v[222:225], v[30:33]
	v_mfma_f32_16x16x32_bf16 v[22:25], v[156:159], v[222:225], v[22:25]
	v_mfma_f32_16x16x32_bf16 v[14:17], v[148:151], v[230:233], v[14:17]
	v_mfma_f32_16x16x32_bf16 v[6:9], v[156:159], v[230:233], v[6:9]
	s_setprio 0
	s_setprio 1
	v_mfma_f32_16x16x32_bf16 v[58:61], v[170:173], v[186:189], v[58:61]
	v_mfma_f32_16x16x32_bf16 v[50:53], v[178:181], v[186:189], v[50:53]
	v_mfma_f32_16x16x32_bf16 v[42:45], v[170:173], v[210:213], v[42:45]
	v_mfma_f32_16x16x32_bf16 v[34:37], v[178:181], v[210:213], v[34:37]
	v_mfma_f32_16x16x32_bf16 v[26:29], v[170:173], v[218:221], v[26:29]
	v_mfma_f32_16x16x32_bf16 v[18:21], v[178:181], v[218:221], v[18:21]
	v_mfma_f32_16x16x32_bf16 v[10:13], v[170:173], v[226:229], v[10:13]
	v_mfma_f32_16x16x32_bf16 v[2:5], v[178:181], v[226:229], v[2:5]
	v_mfma_f32_16x16x32_bf16 v[58:61], v[174:177], v[206:209], v[58:61]
	v_mfma_f32_16x16x32_bf16 v[50:53], v[182:185], v[206:209], v[50:53]
	v_mfma_f32_16x16x32_bf16 v[42:45], v[174:177], v[214:217], v[42:45]
	v_mfma_f32_16x16x32_bf16 v[34:37], v[182:185], v[214:217], v[34:37]
	v_mfma_f32_16x16x32_bf16 v[26:29], v[174:177], v[222:225], v[26:29]
	v_mfma_f32_16x16x32_bf16 v[18:21], v[182:185], v[222:225], v[18:21]
	v_mfma_f32_16x16x32_bf16 v[10:13], v[174:177], v[230:233], v[10:13]
	v_mfma_f32_16x16x32_bf16 v[2:5], v[182:185], v[230:233], v[2:5]
	s_setprio 0
	s_barrier
	s_add_i32 s47, s47, 2
	s_add_u32 s20, s20, 0x100
	s_addc_u32 s21, s21, 0
	s_add_u32 s45, s45, 0x100
	s_addc_u32 s46, s46, 0
	s_cmp_gt_u32 s47, 13
	s_branch .LBB0_611
